# v40 stack + staggered (non-aligned) epilogues in P1/P3/P4
# baseline (speedup 1.0000x reference)
; __device__ __forceinline__ int lane_id() { int l; asm volatile("v_mbcnt_lo_u32_b32 %0, -1, 0\n\tv_mbcnt_hi_u32_b32 %0, -1, %0" : "=v"(l)); return l; }
; __device__ __forceinline__ u32x2 pk4(f32x4 v) { u32x2 w; w.x = pk2(v[0], v[1]); w.y = pk2(v[2], v[3]); return w; }
; #define PG8_BAR __builtin_amdgcn_s_barrier()
;     __device__ __forceinline__ void operator()(const f32x4 (&acc)[2][2][4][2], const Unit& u, int wr, int wc, int fr, int fq) const {
;         const int mode = u.mode;
;         const int loff = (wr * 4 + wc) * (32 * 64) + fq * 16 + fr;
;         u32x2* tg = tb_ + loff; u32x2* tm = tb_ + 32 * 512 + loff;
;         asm volatile("" : "+v"(tg), "+v"(tm));
;         if (mode == 0) {
; #pragma unroll
;             for (int ai = 0; ai < 2; ++ai)
; #pragma unroll
;                 for (int bj = 0; bj < 2; ++bj)
; #pragma unroll
;                     for (int m = 0; m < 4; ++m)
; #pragma unroll
;                         for (int n = 0; n < 2; ++n) { const int idx = ((ai * 2 + bj) * 4 + m) * 2 + n; f32x4 a = acc[ai][bj][m][n], sg;
; #pragma unroll
;                             for (int e = 0; e < 4; ++e) sg[e] = __builtin_amdgcn_rcpf(1.0f + __builtin_amdgcn_exp2f((-1.4426950408889634f / 32.0f) * a[e]));
;                             tg[idx * 64] = pk4(sg); if (n) asm volatile("" ::: "memory"); }
;         } else {
;             const int row0 = u.pm * BM + wr * 64 + fr, col0 = u.pn * BM + wc * 32 + 8 * fq;
; #pragma unroll
;             for (int ai = 0; ai < 2; ++ai) {
;                 u32x2 g[16], t[16];
; #pragma unroll
;                 for (int k = 0; k < 16; ++k) { g[k] = tg[(ai * 16 + k) * 64]; if (mode != 1) t[k] = tm[(ai * 16 + k) * 64]; }
; template <class Epi, class SchedT, bool ALIGN_EPI, bool SP2, bool FP8 = false>
; __device__ __forceinline__ void gemm_phase(LAS unsigned char* lds, const Gemm g, const SchedT& S, const Epi& E, const int wid) {
;     ...
;         if constexpr (ALIGN_EPI) { if (wr == 0) PG8_BAR; }
;         { const int l2_ = lane_id(); E(acc, cur, wr, wc, l2_ & 15, l2_ >> 4); }
.LBB0_541:
.LBB0_542:
	v_mbcnt_lo_u32_b32 v219, -1, 0
	v_mbcnt_hi_u32_b32 v219, -1, v219
	s_cmp_lg_u32 s70, 0
	v_and_b32_e32 v128, 15, v219
	v_and_b32_e32 v134, -16, v219
	v_or_b32_e32 v135, s25, v128
	v_add_u32_e32 v134, v135, v134
	v_ashrrev_i32_e32 v135, 31, v134
	v_lshlrev_b64 v[136:137], 3, v[134:135]
	v_lshl_add_u64 v[134:135], s[40:41], 0, v[136:137]
	v_lshl_add_u64 v[136:137], s[42:43], 0, v[136:137]
	s_cbranch_scc0 .LBB0_677
	flat_load_dwordx2 v[144:145], v[134:135]
	s_cmp_lg_u32 s70, 1
	s_cselect_b64 s[10:11], -1, 0
	s_cmp_eq_u32 s70, 1
	s_cbranch_scc1 .LBB0_545
	flat_load_dwordx2 v[172:173], v[136:137]

; #define PG8_BAR __builtin_amdgcn_s_barrier()
; template <class Epi, class SchedT, bool ALIGN_EPI, bool SP2, bool FP8 = false>
; __device__ __forceinline__ void gemm_phase(LAS unsigned char* lds, const Gemm g, const SchedT& S, const Epi& E, const int wid) {
;     ...
;         if (!has_next) break;
; #pragma unroll
;         for (int a = 0; a < 2; ++a)
; #pragma unroll
;             for (int b = 0; b < 2; ++b)
; #pragma unroll
;                 for (int m = 0; m < 4; ++m)
; #pragma unroll
;                     for (int n = 0; n < 2; ++n) acc[a][b][m][n] = (f32x4){0.f, 0.f, 0.f, 0.f};
;         cur = nxt; cA = nA; cB = nB; ++ui;
;         if constexpr (ALIGN_EPI) { if (wr == 1) PG8_BAR; }
;     }
.LBB0_671:
	s_and_b64 vcc, exec, s[6:7]
	s_mov_b64 s[6:7], -1
	s_cbranch_vccnz .LBB0_527
	s_and_b64 vcc, exec, s[4:5]
	s_cbranch_vccnz .LBB0_526
	s_branch .LBB0_526

;     __device__ __forceinline__ void operator()(const f32x4 (&acc)[2][2][4][2], const Unit& u, int wr, int wc, int fr, int fq) const {
;         const int row0 = u.pm * BM + wr * 64 + fr, col0 = u.pn * BM + wc * 32 + 4 * fq;
; #pragma unroll
;         for (int ai = 0; ai < 2; ++ai)
; #pragma unroll
;             for (int m = 0; m < 4; ++m) { const int row = row0 + ai * HALF + m * 16;
;                 const float* xr = (row < TP ? xp + (size_t)row * DM : xs + (size_t)(row - TP) * DM) + col0;
;                 bf16_t* brow = x1b + (size_t)row * DM + col0; float ss = 0.f;
.LBB0_781:
.LBB0_782:
	s_lshl_b32 s9, s40, 8
	s_add_i32 s9, s9, s91
	v_mbcnt_lo_u32_b32 v26, -1, 0
	v_mbcnt_hi_u32_b32 v26, -1, v26
	s_nop 0
	v_and_or_b32 v16, v26, 15, s9
	v_cmp_lt_i32_e32 vcc, s34, v16
	s_and_saveexec_b64 s[20:21], vcc
	s_xor_b64 s[52:53], exec, s[20:21]
	s_cbranch_execz .LBB0_784
	v_add_u32_e32 v128, 0xffff0000, v16
	v_readlane_b32 s56, v249, 3
	v_lshlrev_b64 v[18:19], 12, v[128:129]
	v_readlane_b32 s58, v249, 5
	v_readlane_b32 s59, v249, 6
	v_readlane_b32 s57, v249, 4
	v_readlane_b32 s60, v249, 7
	v_readlane_b32 s61, v249, 8
	v_readlane_b32 s62, v249, 9
	v_readlane_b32 s63, v249, 10
	v_readlane_b32 s64, v249, 11
	v_readlane_b32 s65, v249, 12
	v_readlane_b32 s66, v249, 13
	v_readlane_b32 s67, v249, 14
	v_readlane_b32 s68, v249, 15
	v_readlane_b32 s69, v249, 16
	v_readlane_b32 s70, v249, 17
	v_readlane_b32 s71, v249, 18
	v_lshl_add_u64 v[24:25], s[58:59], 0, v[18:19]
	v_mov_b32_e32 v17, v129

; #define PG8_BAR __builtin_amdgcn_s_barrier()
; template <class Epi, class SchedT, bool ALIGN_EPI, bool SP2, bool FP8 = false>
; __device__ __forceinline__ void gemm_phase(LAS unsigned char* lds, const Gemm g, const SchedT& S, const Epi& E, const int wid) {
;     ...
;         if (!has_next) break;
; #pragma unroll
;         for (int a = 0; a < 2; ++a)
; #pragma unroll
;             for (int b = 0; b < 2; ++b)
; #pragma unroll
;                 for (int m = 0; m < 4; ++m)
; #pragma unroll
;                     for (int n = 0; n < 2; ++n) acc[a][b][m][n] = (f32x4){0.f, 0.f, 0.f, 0.f};
;         cur = nxt; cA = nA; cB = nB; ++ui;
;         if constexpr (ALIGN_EPI) { if (wr == 1) PG8_BAR; }
;     }
.LBB0_830:
	s_or_b64 exec, exec, s[8:9]
	s_andn2_b64 vcc, exec, s[6:7]
	s_mov_b64 s[6:7], -1
	s_cbranch_vccnz .LBB0_774
	s_and_b64 vcc, exec, s[4:5]
	s_cbranch_vccnz .LBB0_773
	s_branch .LBB0_773
